# v020 + attention: next-tile LDS-DMA loads issued one per MFMA group inside the PV block instead of between softmax and PV
# speedup vs baseline: 1.0009x; 1.0009x over previous
.LBB0_2759:
	v_exp_f32_e32 v2, v4
	s_add_i32 s8, s22, 0
	s_add_i32 s8, s8, 0x10000
	v_add_f32_e32 v8, v2, v209
	v_cvt_pk_bf16_f32 v149, v192, v2
	s_waitcnt lgkmcnt(0)
	v_add_u32_e32 v2, s8, v252
	ds_read_b64_tr_b16 v[150:151], v2 offset:0
	ds_read_b64_tr_b16 v[152:153], v2 offset:0x1000
	ds_read_b64_tr_b16 v[154:155], v2 offset:0x2000
	ds_read_b64_tr_b16 v[156:157], v2 offset:0x3000
	ds_read_b64_tr_b16 v[158:159], v2 offset:0x4000
	ds_read_b64_tr_b16 v[160:161], v2 offset:0x5000
	ds_read_b64_tr_b16 v[162:163], v2 offset:0x6000
	ds_read_b64_tr_b16 v[164:165], v2 offset:0x7000
	v_add_f32_e32 v7, v7, v8
	v_add_f32_e32 v250, v250, v7
	v_cvt_pk_bf16_f32 v4, v194, v195
	v_cvt_pk_bf16_f32 v5, v196, v197
	v_cvt_pk_bf16_f32 v6, v198, v199
	v_cvt_pk_bf16_f32 v7, v200, v201
	v_cvt_pk_bf16_f32 v8, v202, v203
	v_cvt_pk_bf16_f32 v9, v204, v205
	v_cvt_pk_bf16_f32 v10, v206, v207
	v_cvt_pk_bf16_f32 v11, v208, v209
	v_cvt_pk_bf16_f32 v12, v178, v179
	v_cvt_pk_bf16_f32 v13, v180, v181
	v_cvt_pk_bf16_f32 v14, v182, v183
	v_cvt_pk_bf16_f32 v15, v184, v185
	v_cvt_pk_bf16_f32 v146, v186, v187
	v_cvt_pk_bf16_f32 v147, v188, v189
	v_cvt_pk_bf16_f32 v148, v190, v191
	v_lshl_add_u32 v16, v242, 5, s32
	ds_read_b128 v[196:199], v16
	ds_read_b128 v[200:203], v16 offset:16
	ds_read_b64_tr_b16 v[166:167], v2 offset:0x200
	ds_read_b64_tr_b16 v[168:169], v2 offset:0x1200
	ds_read_b64_tr_b16 v[170:171], v2 offset:0x2200
	ds_read_b64_tr_b16 v[172:173], v2 offset:0x3200
	ds_read_b64_tr_b16 v[174:175], v2 offset:0x4200
	ds_read_b64_tr_b16 v[176:177], v2 offset:0x5200
	ds_read_b64_tr_b16 v[178:179], v2 offset:0x6200
	ds_read_b64_tr_b16 v[180:181], v2 offset:0x7200
	s_waitcnt lgkmcnt(8)
	v_mfma_f32_32x32x16_bf16 v[114:129], v[4:7], v[150:153], v[114:129]
	v_mfma_f32_32x32x16_bf16 v[114:129], v[8:11], v[154:157], v[114:129]
	v_mfma_f32_32x32x16_bf16 v[114:129], v[12:15], v[158:161], v[114:129]
	v_mfma_f32_32x32x16_bf16 v[114:129], v[146:149], v[162:165], v[114:129]
	s_cmp_ge_i32 s19, s16
	s_cbranch_scc1 .Lpvd_0
	s_add_i32 s10, s80, s20
	s_add_i32 s10, s10, 64
	s_lshl_b32 s10, s10, 12
	s_add_u32 s98, s2, s10
	s_addc_u32 s99, s3, 0
	s_add_i32 s9, s21, 0x8000
	s_and_b32 s9, s9, 0x8000
	s_add_i32 m0, s9, s81
	s_nop 0
	global_load_lds_dwordx4 v196, s[98:99]
.Lpvd_0:
	ds_read_b64_tr_b16 v[150:151], v2 offset:0x400
	ds_read_b64_tr_b16 v[152:153], v2 offset:0x1400
	ds_read_b64_tr_b16 v[154:155], v2 offset:0x2400
	ds_read_b64_tr_b16 v[156:157], v2 offset:0x3400
	ds_read_b64_tr_b16 v[158:159], v2 offset:0x4400
	ds_read_b64_tr_b16 v[160:161], v2 offset:0x5400
	ds_read_b64_tr_b16 v[162:163], v2 offset:0x6400
	ds_read_b64_tr_b16 v[164:165], v2 offset:0x7400
	s_waitcnt lgkmcnt(8)
	v_mfma_f32_32x32x16_bf16 v[98:113], v[4:7], v[166:169], v[98:113]
	v_mfma_f32_32x32x16_bf16 v[98:113], v[8:11], v[170:173], v[98:113]
	v_mfma_f32_32x32x16_bf16 v[98:113], v[12:15], v[174:177], v[98:113]
	v_mfma_f32_32x32x16_bf16 v[98:113], v[146:149], v[178:181], v[98:113]
	s_cmp_ge_i32 s19, s16
	s_cbranch_scc1 .Lpvd_1
	s_add_i32 s10, s80, s20
	s_add_i32 s10, s10, 64
	s_lshl_b32 s10, s10, 12
	s_add_u32 s98, s2, s10
	s_addc_u32 s99, s3, 0
	s_add_i32 s9, s21, 0x8000
	s_and_b32 s9, s9, 0x8000
	s_add_i32 m0, s9, s83
	s_nop 0
	global_load_lds_dwordx4 v197, s[98:99]
.Lpvd_1:
	ds_read_b64_tr_b16 v[166:167], v2 offset:0x600
	ds_read_b64_tr_b16 v[168:169], v2 offset:0x1600
	ds_read_b64_tr_b16 v[170:171], v2 offset:0x2600
	ds_read_b64_tr_b16 v[172:173], v2 offset:0x3600
	ds_read_b64_tr_b16 v[174:175], v2 offset:0x4600
	ds_read_b64_tr_b16 v[176:177], v2 offset:0x5600
	ds_read_b64_tr_b16 v[178:179], v2 offset:0x6600
	ds_read_b64_tr_b16 v[180:181], v2 offset:0x7600
	s_waitcnt lgkmcnt(8)
	v_mfma_f32_32x32x16_bf16 v[130:145], v[4:7], v[150:153], v[130:145]
	v_mfma_f32_32x32x16_bf16 v[130:145], v[8:11], v[154:157], v[130:145]
	v_mfma_f32_32x32x16_bf16 v[130:145], v[12:15], v[158:161], v[130:145]
	v_mfma_f32_32x32x16_bf16 v[130:145], v[146:149], v[162:165], v[130:145]
	s_cmp_ge_i32 s19, s16
	s_cbranch_scc1 .Lpvd_2
	s_add_i32 s10, s80, s20
	s_add_i32 s10, s10, 64
	s_lshl_b32 s10, s10, 12
	s_add_u32 s98, s2, s10
	s_addc_u32 s99, s3, 0
	s_add_i32 s9, s21, 0x8000
	s_and_b32 s9, s9, 0x8000
	s_add_i32 m0, s9, s87
	s_nop 0
	global_load_lds_dwordx4 v198, s[98:99]
.Lpvd_2:
	ds_read_b64_tr_b16 v[150:151], v2 offset:0x800
	ds_read_b64_tr_b16 v[152:153], v2 offset:0x1800
	ds_read_b64_tr_b16 v[154:155], v2 offset:0x2800
	ds_read_b64_tr_b16 v[156:157], v2 offset:0x3800
	ds_read_b64_tr_b16 v[158:159], v2 offset:0x4800
	ds_read_b64_tr_b16 v[160:161], v2 offset:0x5800
	ds_read_b64_tr_b16 v[162:163], v2 offset:0x6800
	ds_read_b64_tr_b16 v[164:165], v2 offset:0x7800
	s_waitcnt lgkmcnt(8)
	v_mfma_f32_32x32x16_bf16 v[82:97], v[4:7], v[166:169], v[82:97]
	v_mfma_f32_32x32x16_bf16 v[82:97], v[8:11], v[170:173], v[82:97]
	v_mfma_f32_32x32x16_bf16 v[82:97], v[12:15], v[174:177], v[82:97]
	v_mfma_f32_32x32x16_bf16 v[82:97], v[146:149], v[178:181], v[82:97]
	s_cmp_ge_i32 s19, s16
	s_cbranch_scc1 .Lpvd_3
	s_add_i32 s10, s80, s20
	s_add_i32 s10, s10, 64
	s_lshl_b32 s10, s10, 12
	s_add_u32 s98, s2, s10
	s_addc_u32 s99, s3, 0
	s_add_i32 s9, s21, 0x8000
	s_and_b32 s9, s9, 0x8000
	s_add_i32 m0, s9, s91
	s_nop 0
	global_load_lds_dwordx4 v199, s[98:99]
.Lpvd_3:
	ds_read_b64_tr_b16 v[166:167], v2 offset:0xa00
	ds_read_b64_tr_b16 v[168:169], v2 offset:0x1a00
	ds_read_b64_tr_b16 v[170:171], v2 offset:0x2a00
	ds_read_b64_tr_b16 v[172:173], v2 offset:0x3a00
	ds_read_b64_tr_b16 v[174:175], v2 offset:0x4a00
	ds_read_b64_tr_b16 v[176:177], v2 offset:0x5a00
	ds_read_b64_tr_b16 v[178:179], v2 offset:0x6a00
	ds_read_b64_tr_b16 v[180:181], v2 offset:0x7a00
	s_waitcnt lgkmcnt(8)
	v_mfma_f32_32x32x16_bf16 v[66:81], v[4:7], v[150:153], v[66:81]
	v_mfma_f32_32x32x16_bf16 v[66:81], v[8:11], v[154:157], v[66:81]
	v_mfma_f32_32x32x16_bf16 v[66:81], v[12:15], v[158:161], v[66:81]
	v_mfma_f32_32x32x16_bf16 v[66:81], v[146:149], v[162:165], v[66:81]
	s_cmp_ge_i32 s19, s16
	s_cbranch_scc1 .Lpvd_4
	s_add_i32 s10, s54, s20
	s_lshl_b32 s10, s10, 12
	s_add_u32 s98, s4, s10
	s_addc_u32 s99, s5, 0
	s_add_i32 s9, s21, 0x8000
	s_and_b32 s9, s9, 0x8000
	s_add_i32 s9, s42, s9
	s_add_i32 m0, s9, 0
	s_nop 0
	global_load_lds_dwordx4 v200, s[98:99]
.Lpvd_4:
	ds_read_b64_tr_b16 v[150:151], v2 offset:0xc00
	ds_read_b64_tr_b16 v[152:153], v2 offset:0x1c00
	ds_read_b64_tr_b16 v[154:155], v2 offset:0x2c00
	ds_read_b64_tr_b16 v[156:157], v2 offset:0x3c00
	ds_read_b64_tr_b16 v[158:159], v2 offset:0x4c00
	ds_read_b64_tr_b16 v[160:161], v2 offset:0x5c00
	ds_read_b64_tr_b16 v[162:163], v2 offset:0x6c00
	ds_read_b64_tr_b16 v[164:165], v2 offset:0x7c00
	s_waitcnt lgkmcnt(8)
	v_mfma_f32_32x32x16_bf16 v[50:65], v[4:7], v[166:169], v[50:65]
	v_mfma_f32_32x32x16_bf16 v[50:65], v[8:11], v[170:173], v[50:65]
	v_mfma_f32_32x32x16_bf16 v[50:65], v[12:15], v[174:177], v[50:65]
	v_mfma_f32_32x32x16_bf16 v[50:65], v[146:149], v[178:181], v[50:65]
	s_cmp_ge_i32 s19, s16
	s_cbranch_scc1 .Lpvd_5
	s_add_i32 s10, s54, s20
	s_lshl_b32 s10, s10, 12
	s_add_u32 s98, s4, s10
	s_addc_u32 s99, s5, 0
	s_add_i32 s9, s21, 0x8000
	s_and_b32 s9, s9, 0x8000
	s_add_i32 s9, s42, s9
	s_add_i32 m0, s9, 0x400
	s_nop 0
	global_load_lds_dwordx4 v201, s[98:99]
.Lpvd_5:
	ds_read_b64_tr_b16 v[166:167], v2 offset:0xe00
	ds_read_b64_tr_b16 v[168:169], v2 offset:0x1e00
	ds_read_b64_tr_b16 v[170:171], v2 offset:0x2e00
	ds_read_b64_tr_b16 v[172:173], v2 offset:0x3e00
	ds_read_b64_tr_b16 v[174:175], v2 offset:0x4e00
	ds_read_b64_tr_b16 v[176:177], v2 offset:0x5e00
	ds_read_b64_tr_b16 v[178:179], v2 offset:0x6e00
	ds_read_b64_tr_b16 v[180:181], v2 offset:0x7e00
	s_waitcnt lgkmcnt(8)
	v_mfma_f32_32x32x16_bf16 v[34:49], v[4:7], v[150:153], v[34:49]
	v_mfma_f32_32x32x16_bf16 v[34:49], v[8:11], v[154:157], v[34:49]
	v_mfma_f32_32x32x16_bf16 v[34:49], v[12:15], v[158:161], v[34:49]
	v_mfma_f32_32x32x16_bf16 v[34:49], v[146:149], v[162:165], v[34:49]
	s_cmp_ge_i32 s19, s16
	s_cbranch_scc1 .Lpvd_6
	s_add_i32 s10, s54, s20
	s_lshl_b32 s10, s10, 12
	s_add_u32 s98, s4, s10
	s_addc_u32 s99, s5, 0
	s_add_i32 s9, s21, 0x8000
	s_and_b32 s9, s9, 0x8000
	s_add_i32 s9, s42, s9
	s_add_i32 m0, s9, 0x800
	s_nop 0
	global_load_lds_dwordx4 v202, s[98:99]
.Lpvd_6:
	s_waitcnt lgkmcnt(0)
	v_mfma_f32_32x32x16_bf16 v[18:33], v[4:7], v[166:169], v[18:33]
	v_mfma_f32_32x32x16_bf16 v[18:33], v[8:11], v[170:173], v[18:33]
	v_mfma_f32_32x32x16_bf16 v[18:33], v[12:15], v[174:177], v[18:33]
	v_mfma_f32_32x32x16_bf16 v[18:33], v[146:149], v[178:181], v[18:33]
	s_cmp_ge_i32 s19, s16
	s_cbranch_scc1 .Lpvd_7
	s_add_i32 s10, s54, s20
	s_lshl_b32 s10, s10, 12
	s_add_u32 s98, s4, s10
	s_addc_u32 s99, s5, 0
	s_add_i32 s9, s21, 0x8000
	s_and_b32 s9, s9, 0x8000
	s_add_i32 s9, s42, s9
	s_add_i32 m0, s9, 0xc00
	s_nop 0
	global_load_lds_dwordx4 v203, s[98:99]
.Lpvd_7:
.LBB0_2760:
	s_waitcnt vmcnt(0)
	s_add_i32 s21, s21, 0x8000
	s_add_i32 s20, s20, 64
	s_cmp_eq_u32 s16, s19
	s_waitcnt vmcnt(0) lgkmcnt(0)
	s_barrier
	s_cbranch_scc1 .LBB0_2780

.LBB0_2777:
	v_sub_f32_e32 v4, v253, v251
	v_fmamk_f32 v2, v162, 0x3e0293ee, v4
	v_exp_f32_e32 v194, v2
	v_fmamk_f32 v2, v146, 0x3e0293ee, v4
	v_exp_f32_e32 v178, v2
	v_fmamk_f32 v2, v163, 0x3e0293ee, v4
	v_exp_f32_e32 v195, v2
	v_fmamk_f32 v2, v147, 0x3e0293ee, v4
	v_exp_f32_e32 v179, v2
	v_fmamk_f32 v2, v164, 0x3e0293ee, v4
	v_exp_f32_e32 v196, v2
	v_fmamk_f32 v2, v148, 0x3e0293ee, v4
	v_exp_f32_e32 v180, v2
	v_fmamk_f32 v2, v165, 0x3e0293ee, v4
	v_exp_f32_e32 v197, v2
	v_fmamk_f32 v2, v149, 0x3e0293ee, v4
	v_exp_f32_e32 v181, v2
	v_pk_add_f32 v[6:7], v[194:195], v[178:179]
	v_fmamk_f32 v2, v166, 0x3e0293ee, v4
	v_exp_f32_e32 v198, v2
	v_fmamk_f32 v2, v150, 0x3e0293ee, v4
	v_exp_f32_e32 v182, v2
	v_fmamk_f32 v2, v167, 0x3e0293ee, v4
	v_exp_f32_e32 v199, v2
	v_fmamk_f32 v2, v151, 0x3e0293ee, v4
	v_exp_f32_e32 v183, v2
	v_pk_add_f32 v[6:7], v[6:7], v[196:197]
	v_pk_add_f32 v[6:7], v[6:7], v[180:181]
	v_fmamk_f32 v2, v168, 0x3e0293ee, v4
	v_exp_f32_e32 v200, v2
	v_fmamk_f32 v2, v152, 0x3e0293ee, v4
	v_exp_f32_e32 v184, v2
	v_fmamk_f32 v2, v169, 0x3e0293ee, v4
	v_exp_f32_e32 v201, v2
	v_fmamk_f32 v2, v153, 0x3e0293ee, v4
	v_exp_f32_e32 v185, v2
	v_pk_add_f32 v[6:7], v[6:7], v[198:199]
	v_pk_add_f32 v[6:7], v[6:7], v[182:183]
	v_fmamk_f32 v2, v170, 0x3e0293ee, v4
	v_exp_f32_e32 v202, v2
	v_fmamk_f32 v2, v154, 0x3e0293ee, v4
	v_exp_f32_e32 v186, v2
	v_fmamk_f32 v2, v171, 0x3e0293ee, v4
	v_exp_f32_e32 v203, v2
	v_fmamk_f32 v2, v155, 0x3e0293ee, v4
	v_exp_f32_e32 v187, v2
	v_pk_add_f32 v[6:7], v[6:7], v[200:201]
	v_pk_add_f32 v[6:7], v[6:7], v[184:185]
	v_fmamk_f32 v2, v172, 0x3e0293ee, v4
	v_exp_f32_e32 v204, v2
	v_fmamk_f32 v2, v156, 0x3e0293ee, v4
	v_exp_f32_e32 v188, v2
	v_fmamk_f32 v2, v173, 0x3e0293ee, v4
	v_exp_f32_e32 v205, v2
	v_fmamk_f32 v2, v157, 0x3e0293ee, v4
	v_exp_f32_e32 v189, v2
	v_pk_add_f32 v[6:7], v[6:7], v[202:203]
	v_pk_add_f32 v[6:7], v[6:7], v[186:187]
	v_fmamk_f32 v2, v174, 0x3e0293ee, v4
	v_exp_f32_e32 v206, v2
	v_fmamk_f32 v2, v158, 0x3e0293ee, v4
	v_exp_f32_e32 v190, v2
	v_fmamk_f32 v2, v175, 0x3e0293ee, v4
	v_exp_f32_e32 v207, v2
	v_fmamk_f32 v2, v159, 0x3e0293ee, v4
	v_exp_f32_e32 v191, v2
	v_pk_add_f32 v[6:7], v[6:7], v[204:205]
	v_pk_add_f32 v[6:7], v[6:7], v[188:189]
	v_fmamk_f32 v2, v176, 0x3e0293ee, v4
	v_exp_f32_e32 v208, v2
	v_fmamk_f32 v2, v160, 0x3e0293ee, v4
	v_exp_f32_e32 v192, v2
	v_fmamk_f32 v2, v177, 0x3e0293ee, v4
	v_exp_f32_e32 v209, v2
	v_pk_add_f32 v[6:7], v[6:7], v[206:207]
	v_pk_add_f32 v[6:7], v[6:7], v[190:191]
	v_fmac_f32_e32 v4, 0x3e0293ee, v161
	v_add_f32_e32 v7, v6, v7
	v_add_f32_e32 v7, v7, v208
	v_add_f32_e32 v7, v7, v192
	s_add_i32 s19, s19, 1
	s_cmp_ge_i32 s19, s16
	s_cbranch_scc1 .LBB0_2759
.LBB0_2778:
	s_branch .LBB0_2759
.LBB0_2779:
	v_mov_b32_e32 v16, v3
	v_mov_b32_e32 v17, v3
	v_mov_b32_e32 v2, v3
	v_mov_b32_e32 v4, v3
	v_mov_b32_e32 v5, v3
	v_mov_b32_e32 v6, v3
	v_mov_b32_e32 v7, v3
	v_mov_b32_e32 v8, v3
	v_mov_b32_e32 v9, v3
	v_mov_b32_e32 v10, v3
	v_mov_b32_e32 v11, v3
	v_mov_b32_e32 v12, v3
	v_mov_b32_e32 v13, v3
	v_mov_b32_e32 v14, v3
	v_mov_b32_e32 v15, v3
	v_mov_b64_e32 v[32:33], v[16:17]
	v_mov_b64_e32 v[48:49], v[16:17]
	v_mov_b64_e32 v[64:65], v[16:17]
	v_mov_b64_e32 v[80:81], v[16:17]
	v_mov_b64_e32 v[96:97], v[16:17]
	v_mov_b64_e32 v[144:145], v[16:17]
	v_mov_b64_e32 v[112:113], v[16:17]
	v_mov_b64_e32 v[128:129], v[16:17]
	v_mov_b32_e32 v250, 0
	v_mov_b64_e32 v[30:31], v[14:15]
	v_mov_b64_e32 v[28:29], v[12:13]
	v_mov_b64_e32 v[26:27], v[10:11]
	v_mov_b64_e32 v[24:25], v[8:9]
	v_mov_b64_e32 v[22:23], v[6:7]
	v_mov_b64_e32 v[20:21], v[4:5]
	v_mov_b64_e32 v[18:19], v[2:3]
	v_mov_b64_e32 v[46:47], v[14:15]
	v_mov_b64_e32 v[44:45], v[12:13]
	v_mov_b64_e32 v[42:43], v[10:11]
	v_mov_b64_e32 v[40:41], v[8:9]
	v_mov_b64_e32 v[38:39], v[6:7]
	v_mov_b64_e32 v[36:37], v[4:5]
	v_mov_b64_e32 v[34:35], v[2:3]
	v_mov_b64_e32 v[62:63], v[14:15]
	v_mov_b64_e32 v[60:61], v[12:13]
	v_mov_b64_e32 v[58:59], v[10:11]
	v_mov_b64_e32 v[56:57], v[8:9]
	v_mov_b64_e32 v[54:55], v[6:7]
	v_mov_b64_e32 v[52:53], v[4:5]
	v_mov_b64_e32 v[50:51], v[2:3]
	v_mov_b64_e32 v[78:79], v[14:15]
	v_mov_b64_e32 v[76:77], v[12:13]
	v_mov_b64_e32 v[74:75], v[10:11]
	v_mov_b64_e32 v[72:73], v[8:9]
	v_mov_b64_e32 v[70:71], v[6:7]
	v_mov_b64_e32 v[68:69], v[4:5]
	v_mov_b64_e32 v[66:67], v[2:3]
	v_mov_b64_e32 v[94:95], v[14:15]
	v_mov_b64_e32 v[92:93], v[12:13]
	v_mov_b64_e32 v[90:91], v[10:11]
	v_mov_b64_e32 v[88:89], v[8:9]
	v_mov_b64_e32 v[86:87], v[6:7]
	v_mov_b64_e32 v[84:85], v[4:5]
	v_mov_b64_e32 v[82:83], v[2:3]
	v_mov_b64_e32 v[142:143], v[14:15]
	v_mov_b64_e32 v[140:141], v[12:13]
	v_mov_b64_e32 v[138:139], v[10:11]
	v_mov_b64_e32 v[136:137], v[8:9]
	v_mov_b64_e32 v[134:135], v[6:7]
	v_mov_b64_e32 v[132:133], v[4:5]
	v_mov_b64_e32 v[130:131], v[2:3]
	v_mov_b64_e32 v[110:111], v[14:15]
	v_mov_b64_e32 v[108:109], v[12:13]
	v_mov_b64_e32 v[106:107], v[10:11]
	v_mov_b64_e32 v[104:105], v[8:9]
	v_mov_b64_e32 v[102:103], v[6:7]
	v_mov_b64_e32 v[100:101], v[4:5]
	v_mov_b64_e32 v[98:99], v[2:3]
	v_mov_b64_e32 v[126:127], v[14:15]
	v_mov_b64_e32 v[124:125], v[12:13]
	v_mov_b64_e32 v[122:123], v[10:11]
	v_mov_b64_e32 v[120:121], v[8:9]
	v_mov_b64_e32 v[118:119], v[6:7]
	v_mov_b64_e32 v[116:117], v[4:5]
	v_mov_b64_e32 v[114:115], v[2:3]
